# v43 + prep item order: odd blocks >= 64 run their three light items first and their DFT item last (DFT items of half the blocks de-phased)
# baseline (speedup 1.0000x reference)
; __device__ __forceinline__ int opaque_tid() { int t = threadIdx.x; asm volatile("" : "+v"(t)); return t; }
; __device__ __forceinline__ void phase_prep(const Params& P, int l, unsigned char* lds) {
;     ...
;     for (int item = blockIdx.x; item < ROWS / 64 + NBATCH * 20; item += G) {
;         const int tid = opaque_tid();
;         const int type = item >= ROWS / 64;
;         int r0, b, t0;
;         if (!type) { r0 = item * 64; b = r0 / TT; t0 = r0 - b * TT; }
;         else { const int idx = item - ROWS / 64; b = idx / 20; const int jb = idx - b * 20; t0 = (jb < 4) ? 64 * jb : CTX + 64 * (jb - 4); r0 = b * TT + t0; }
;         const bool is_ctx = t0 < CTX;
.LBB0_228:
	s_mov_b32 s101, s28
	s_cmp_lg_u32 s60, 0x100
	s_cbranch_scc1 .Lprep_map_done
	s_and_b32 s100, s28, 0xff
	s_lshr_b32 s101, s28, 8
	v_readlane_b32 vcc_lo, v255, 0
	s_nop 3
	s_cmp_eq_u32 vcc_lo, 3
	s_cbranch_scc1 .Lprep_last
	s_cmp_lt_u32 s100, 0x40
	s_cbranch_scc1 .Lprep_std
	s_bitcmp1_b32 s100, 0
	s_cbranch_scc0 .Lprep_std
	s_cmp_eq_u32 s101, 3
	s_cbranch_scc1 .Lprep_a0
	s_mul_i32 s101, s101, 0xc0
	s_add_u32 s101, s101, s100
	s_sub_u32 s101, s101, 0x40
	s_branch .Lprep_map_done
.Lprep_std:
	s_cmp_eq_u32 s101, 0
	s_cbranch_scc1 .Lprep_a0
	s_cmp_lt_u32 s100, 0x40
	s_cbranch_scc1 .Lprep_alo
	s_sub_u32 s101, s101, 1
	s_mul_i32 s101, s101, 0xc0
	s_add_u32 s101, s101, s100
	s_sub_u32 s101, s101, 0x40
	s_branch .Lprep_map_done
